# HG_H3 third MFMA block: twelve fragment reads issued up front, MFMAs behind counted lgkmcnt waits
# speedup vs baseline: 1.0035x; 1.0004x over previous
; #define LAS __attribute__((address_space(3)))
; __device__ __forceinline__ unsigned pk2(float lo, float hi) { f32x2c v = {lo, hi}; return __builtin_bit_cast(unsigned, __builtin_convertvector(v, bf16x2c)); }
; __device__ __forceinline__ void hgrn_h3(LAS unsigned char* lds8, const int e) {
;     ...
;         const int fr = lane & 15, fq = lane >> 4;
;         f32x4 acc[4];
; #pragma unroll
;         for (int I = 0; I < 4; ++I) acc[I] = (f32x4){0.f, 0.f, 0.f, 0.f};
; #pragma unroll
;         for (int ks = 0; ks < 4; ++ks) { const bf16x8 a = *(const LAS bf16x8*)(ST + (16 * wave + fr) * RS128 + 32 * ks + 8 * fq);
; #pragma unroll
;             for (int I = 0; I < 4; ++I) { const bf16x8 bb = *(const LAS bf16x8*)(Qb + (16 * I + fr) * RS128 + 32 * ks + 8 * fq);
;                 acc[I] = __builtin_amdgcn_mfma_f32_16x16x32_bf16(a, bb, acc[I], 0, 0, 0); } }
; #pragma unroll
;         for (int I = 0; I < 4; ++I) {
;             const int rb = 8 * I * (I + 1);
;             f32x4 P[4];
; #pragma unroll
;             for (int Jt = 0; Jt < 4; ++Jt) { P[Jt] = (f32x4){0.f, 0.f, 0.f, 0.f};
;                 if (Jt <= I) {
; #pragma unroll
;                     for (int ks = 0; ks < 4; ++ks) { const bf16x8 a = *(const LAS bf16x8*)(KT + (rb + 16 * Jt + fr) * RS128 + 32 * ks + 8 * fq);
;                         const bf16x8 bb = *(const LAS bf16x8*)(Qt + (16 * I + fr) * RS128 + 32 * ks + 8 * fq);
;                         P[Jt] = __builtin_amdgcn_mfma_f32_16x16x32_bf16(a, bb, P[Jt], 0, 0, 0); }
;                     if (Jt == I) {
; #pragma unroll
;                         for (int r = 0; r < 4; ++r) P[Jt][r] = (4 * fq + r <= fr) ? P[Jt][r] : 0.f; }
;                 } }
; #pragma unroll
;             for (int s = 0; s < 2; ++s) if (2 * s <= I) {
;                 u32x4 pw; pw.x = pk2(P[2 * s][0], P[2 * s][1]); pw.y = pk2(P[2 * s][2], P[2 * s][3]); pw.z = pk2(P[2 * s + 1][0], P[2 * s + 1][1]); pw.w = pk2(P[2 * s + 1][2], P[2 * s + 1][3]);
;                 const s16x4 v0 = *(const LAS s16x4*)(VT + (16 * wave + fr) * RS64 + 32 * s + 4 * fq), v1 = *(const LAS s16x4*)(VT + (16 * wave + fr) * RS64 + 32 * s + 16 + 4 * fq);
;                 const bf16x8 a = (bf16x8){v0[0], v0[1], v0[2], v0[3], v1[0], v1[1], v1[2], v1[3]};
;                 acc[I] = __builtin_amdgcn_mfma_f32_16x16x32_bf16(a, __builtin_bit_cast(bf16x8, pw), acc[I], 0, 0, 0); }
.LBB0_754:
	s_or_b64 exec, exec, s[30:31]
	s_waitcnt lgkmcnt(0)
	s_barrier
	ds_read_b128 v[4:7], v53
	ds_read_b128 v[8:11], v79 offset:17408
	ds_read_b128 v[12:15], v79 offset:21760
	ds_read_b128 v[16:19], v79 offset:26112
	ds_read_b128 v[20:23], v79 offset:30464
	ds_read_b128 v[192:195], v53 offset:64
	ds_read_b128 v[196:199], v79 offset:17472
	ds_read_b128 v[200:203], v79 offset:21824
	ds_read_b128 v[204:207], v79 offset:26176
	ds_read_b128 v[208:211], v79 offset:30528
	ds_read_b128 v[212:215], v53 offset:128
	ds_read_b128 v[216:219], v79 offset:17536
	ds_read_b128 v[220:223], v79 offset:21888
	ds_read_b128 v[224:227], v79 offset:26240
	ds_read_b128 v[228:231], v79 offset:30592
	s_waitcnt lgkmcnt(13)
	v_mfma_f32_16x16x32_bf16 v[8:11], v[4:7], v[8:11], 0
	s_add_i32 s66, s66, s46
	s_add_i32 s4, s4, s5
	s_add_i32 s28, s28, s34
	s_waitcnt lgkmcnt(12)
	v_mfma_f32_16x16x32_bf16 v[12:15], v[4:7], v[12:15], 0
	v_lshl_add_u64 v[32:33], v[32:33], 0, s[2:3]
	s_cmpk_lt_i32 s66, 0x400
	s_waitcnt lgkmcnt(11)
	v_mfma_f32_16x16x32_bf16 v[16:19], v[4:7], v[16:19], 0
	s_waitcnt lgkmcnt(10)
	v_mfma_f32_16x16x32_bf16 v[4:7], v[4:7], v[20:23], 0
	ds_read_b128 v[236:239], v53 offset:192
	ds_read_b128 v[240:243], v79 offset:17600
	ds_read_b128 v[244:247], v79 offset:21952
	s_waitcnt lgkmcnt(11)
	v_mfma_f32_16x16x32_bf16 v[8:11], v[192:195], v[196:199], v[8:11]
	s_waitcnt lgkmcnt(10)
	v_mfma_f32_16x16x32_bf16 v[12:15], v[192:195], v[200:203], v[12:15]
	s_waitcnt lgkmcnt(9)
	v_mfma_f32_16x16x32_bf16 v[16:19], v[192:195], v[204:207], v[16:19]
	s_waitcnt lgkmcnt(8)
	v_mfma_f32_16x16x32_bf16 v[4:7], v[192:195], v[208:211], v[4:7]
	s_waitcnt lgkmcnt(6)
	v_mfma_f32_16x16x32_bf16 v[8:11], v[212:215], v[216:219], v[8:11]
	s_waitcnt lgkmcnt(5)
	v_mfma_f32_16x16x32_bf16 v[12:15], v[212:215], v[220:223], v[12:15]
	s_waitcnt lgkmcnt(4)
	v_mfma_f32_16x16x32_bf16 v[16:19], v[212:215], v[224:227], v[16:19]
	s_waitcnt lgkmcnt(3)
	v_mfma_f32_16x16x32_bf16 v[4:7], v[212:215], v[228:231], v[4:7]
	s_waitcnt lgkmcnt(1)
	v_mfma_f32_16x16x32_bf16 v[8:11], v[236:239], v[240:243], v[8:11]
	s_waitcnt lgkmcnt(0)
	v_mfma_f32_16x16x32_bf16 v[82:85], v[236:239], v[244:247], v[12:15]
	s_nop 2
	ds_read_b128 v[12:15], v79 offset:26304
	s_waitcnt lgkmcnt(0)
	v_mfma_f32_16x16x32_bf16 v[20:23], v[236:239], v[12:15], v[16:19]
	ds_read_b128 v[12:15], v79 offset:30656
	s_waitcnt lgkmcnt(0)
	v_mfma_f32_16x16x32_bf16 v[4:7], v[236:239], v[12:15], v[4:7]
	ds_read_b128 v[12:15], v79 offset:34816
	ds_read_b128 v[16:19], v79
	s_waitcnt lgkmcnt(0)
	v_mfma_f32_16x16x32_bf16 v[12:15], v[12:15], v[16:19], 0
	ds_read_b128 v[16:19], v79 offset:34880
	ds_read_b128 v[24:27], v79 offset:64
	s_waitcnt lgkmcnt(0)
	v_mfma_f32_16x16x32_bf16 v[12:15], v[16:19], v[24:27], v[12:15]
	ds_read_b128 v[16:19], v79 offset:34944
	ds_read_b128 v[24:27], v79 offset:128
	s_waitcnt lgkmcnt(0)
	v_mfma_f32_16x16x32_bf16 v[12:15], v[16:19], v[24:27], v[12:15]
	ds_read_b128 v[16:19], v79 offset:35008
	ds_read_b128 v[24:27], v79 offset:192
	s_waitcnt lgkmcnt(0)
	v_mfma_f32_16x16x32_bf16 v[12:15], v[16:19], v[24:27], v[12:15]
	v_mov_b32_e32 v18, v3
	v_mov_b32_e32 v19, v3
	s_nop 5
	v_cndmask_b32_e64 v12, v12, 0, s[20:21]
	v_cndmask_b32_e64 v13, 0, v13, s[22:23]
	v_cndmask_b32_e64 v14, v14, 0, s[24:25]
	v_cndmask_b32_e64 v15, v15, 0, s[26:27]
	v_cvt_pk_bf16_f32 v16, v12, v13
	v_cvt_pk_bf16_f32 v17, v14, v15
	ds_read2_b64 v[12:15], v81 offset1:4
	s_waitcnt lgkmcnt(0)
	v_mfma_f32_16x16x32_bf16 v[8:11], v[12:15], v[16:19], v[8:11]
	ds_read_b128 v[16:19], v79 offset:39168
	ds_read_b128 v[24:27], v79 offset:4352
	ds_read_b128 v[86:89], v79 offset:39232
	ds_read_b128 v[90:93], v79 offset:4416
	ds_read_b128 v[192:195], v79 offset:39296
	ds_read_b128 v[94:97], v79 offset:4480
	ds_read_b128 v[196:199], v79 offset:39360
	ds_read_b128 v[98:101], v79 offset:4544
	ds_read_b128 v[200:203], v79 offset:43520
	ds_read_b128 v[204:207], v79 offset:43584
	ds_read_b128 v[208:211], v79 offset:43648
	ds_read_b128 v[212:215], v79 offset:43712
	s_waitcnt lgkmcnt(10)
	v_mfma_f32_16x16x32_bf16 v[16:19], v[16:19], v[24:27], 0
	s_waitcnt lgkmcnt(8)
	v_mfma_f32_16x16x32_bf16 v[16:19], v[86:89], v[90:93], v[16:19]
	s_waitcnt lgkmcnt(6)
	v_mfma_f32_16x16x32_bf16 v[16:19], v[192:195], v[94:97], v[16:19]
	s_waitcnt lgkmcnt(4)
	v_mfma_f32_16x16x32_bf16 v[16:19], v[196:199], v[98:101], v[16:19]
	s_waitcnt lgkmcnt(3)
	v_mfma_f32_16x16x32_bf16 v[24:27], v[200:203], v[24:27], 0
	s_nop 4
	v_cvt_pk_bf16_f32 v16, v16, v17
	v_cvt_pk_bf16_f32 v17, v18, v19
	s_waitcnt lgkmcnt(2)
	v_mfma_f32_16x16x32_bf16 v[24:27], v[204:207], v[90:93], v[24:27]
	s_waitcnt lgkmcnt(1)
	v_mfma_f32_16x16x32_bf16 v[24:27], v[208:211], v[94:97], v[24:27]
	s_waitcnt lgkmcnt(0)
	v_mfma_f32_16x16x32_bf16 v[24:27], v[212:215], v[98:101], v[24:27]
	s_nop 7
	v_cndmask_b32_e64 v24, v24, 0, s[20:21]
	v_cndmask_b32_e64 v25, 0, v25, s[22:23]
	v_cndmask_b32_e64 v26, v26, 0, s[24:25]
	v_cndmask_b32_e64 v27, v27, 0, s[26:27]
	v_cvt_pk_bf16_f32 v18, v24, v25
	v_cvt_pk_bf16_f32 v19, v26, v27
	s_nop 1
	v_mfma_f32_16x16x32_bf16 v[16:19], v[12:15], v[16:19], v[82:85]
	ds_read_b128 v[24:27], v79 offset:47872
	s_nop 1
	ds_read_b128 v[82:85], v79 offset:8704
	ds_read_b128 v[86:89], v79 offset:47936
	ds_read_b128 v[90:93], v79 offset:8768
	s_waitcnt lgkmcnt(2)
	v_mfma_f32_16x16x32_bf16 v[24:27], v[24:27], v[82:85], 0
	s_waitcnt lgkmcnt(0)
	v_mfma_f32_16x16x32_bf16 v[24:27], v[86:89], v[90:93], v[24:27]
	ds_read_b128 v[86:89], v79 offset:48000
	ds_read_b128 v[94:97], v79 offset:8832
	s_waitcnt lgkmcnt(0)
; #define LAS __attribute__((address_space(3)))
; __device__ __forceinline__ unsigned pk2(float lo, float hi) { f32x2c v = {lo, hi}; return __builtin_bit_cast(unsigned, __builtin_convertvector(v, bf16x2c)); }
; __device__ __forceinline__ void hgrn_h3(LAS unsigned char* lds8, const int e) {
;     ...
;         for (int I = 0; I < 4; ++I) {
;             const int rb = 8 * I * (I + 1);
;             f32x4 P[4];
; #pragma unroll
;             for (int Jt = 0; Jt < 4; ++Jt) { P[Jt] = (f32x4){0.f, 0.f, 0.f, 0.f};
;                 if (Jt <= I) {
; #pragma unroll
;                     for (int ks = 0; ks < 4; ++ks) { const bf16x8 a = *(const LAS bf16x8*)(KT + (rb + 16 * Jt + fr) * RS128 + 32 * ks + 8 * fq);
;                         const bf16x8 bb = *(const LAS bf16x8*)(Qt + (16 * I + fr) * RS128 + 32 * ks + 8 * fq);
;                         P[Jt] = __builtin_amdgcn_mfma_f32_16x16x32_bf16(a, bb, P[Jt], 0, 0, 0); }
;                     if (Jt == I) {
; #pragma unroll
;                         for (int r = 0; r < 4; ++r) P[Jt][r] = (4 * fq + r <= fr) ? P[Jt][r] : 0.f; }
;                 } }
; #pragma unroll
;             for (int s = 0; s < 2; ++s) if (2 * s <= I) {
;                 u32x4 pw; pw.x = pk2(P[2 * s][0], P[2 * s][1]); pw.y = pk2(P[2 * s][2], P[2 * s][3]); pw.z = pk2(P[2 * s + 1][0], P[2 * s + 1][1]); pw.w = pk2(P[2 * s + 1][2], P[2 * s + 1][3]);
;                 const s16x4 v0 = *(const LAS s16x4*)(VT + (16 * wave + fr) * RS64 + 32 * s + 4 * fq), v1 = *(const LAS s16x4*)(VT + (16 * wave + fr) * RS64 + 32 * s + 16 + 4 * fq);
;                 const bf16x8 a = (bf16x8){v0[0], v0[1], v0[2], v0[3], v1[0], v1[1], v1[2], v1[3]};
;                 acc[I] = __builtin_amdgcn_mfma_f32_16x16x32_bf16(a, __builtin_bit_cast(bf16x8, pw), acc[I], 0, 0, 0); }
;         }
; #pragma unroll
;         for (int I = 0; I < 4; ++I) *(f32x4*)(O0 + (size_t)(m0 + 16 * I + fr) * 1024 + h * 128 + 16 * wave + 4 * fq) = acc[I];
	v_mfma_f32_16x16x32_bf16 v[24:27], v[86:89], v[94:97], v[24:27]
	ds_read_b128 v[86:89], v79 offset:48064
	ds_read_b128 v[98:101], v79 offset:8896
	ds_read_b128 v[102:105], v79 offset:52288
	s_waitcnt lgkmcnt(1)
	v_mfma_f32_16x16x32_bf16 v[24:27], v[86:89], v[98:101], v[24:27]
	ds_read_b128 v[86:89], v79 offset:52224
	s_waitcnt lgkmcnt(0)
	v_mfma_f32_16x16x32_bf16 v[86:89], v[86:89], v[82:85], 0
	s_nop 4
	v_cvt_pk_bf16_f32 v24, v24, v25
	v_cvt_pk_bf16_f32 v25, v26, v27
	v_mfma_f32_16x16x32_bf16 v[86:89], v[102:105], v[90:93], v[86:89]
	ds_read_b128 v[102:105], v79 offset:52352
	s_waitcnt lgkmcnt(0)
	v_mfma_f32_16x16x32_bf16 v[86:89], v[102:105], v[94:97], v[86:89]
	ds_read_b128 v[102:105], v79 offset:52416
	s_waitcnt lgkmcnt(0)
	v_mfma_f32_16x16x32_bf16 v[86:89], v[102:105], v[98:101], v[86:89]
	ds_read_b128 v[102:105], v79 offset:56576
	s_nop 6
	v_cvt_pk_bf16_f32 v26, v86, v87
	s_waitcnt lgkmcnt(0)
	v_mfma_f32_16x16x32_bf16 v[82:85], v[102:105], v[82:85], 0
	ds_read_b128 v[102:105], v79 offset:56640
	v_cvt_pk_bf16_f32 v27, v88, v89
	s_waitcnt lgkmcnt(0)
	v_mfma_f32_16x16x32_bf16 v[82:85], v[102:105], v[90:93], v[82:85]
	ds_read_b128 v[90:93], v79 offset:56704
	s_waitcnt lgkmcnt(0)
	v_mfma_f32_16x16x32_bf16 v[82:85], v[90:93], v[94:97], v[82:85]
	ds_read_b128 v[90:93], v79 offset:56768
	v_mfma_f32_16x16x32_bf16 v[20:23], v[12:15], v[24:27], v[20:23]
	ds_read2_b64 v[24:27], v81 offset0:8 offset1:12
	s_waitcnt lgkmcnt(1)
	v_mfma_f32_16x16x32_bf16 v[82:85], v[90:93], v[98:101], v[82:85]
	s_nop 7
	v_cndmask_b32_e64 v82, v82, 0, s[20:21]
	v_cndmask_b32_e64 v83, 0, v83, s[22:23]
	v_cndmask_b32_e64 v84, v84, 0, s[24:25]
	v_cndmask_b32_e64 v85, v85, 0, s[26:27]
	v_cvt_pk_bf16_f32 v82, v82, v83
	v_cvt_pk_bf16_f32 v83, v84, v85
	v_mov_b32_e32 v84, v3
	v_mov_b32_e32 v85, v3
	s_waitcnt lgkmcnt(0)
	s_nop 0
	v_mfma_f32_16x16x32_bf16 v[20:23], v[24:27], v[82:85], v[20:23]
	ds_read_b128 v[82:85], v79 offset:60928
	ds_read_b128 v[86:89], v79 offset:13056
	ds_read_b128 v[90:93], v79 offset:60992
	ds_read_b128 v[94:97], v79 offset:13120
	s_waitcnt lgkmcnt(2)
	v_mfma_f32_16x16x32_bf16 v[82:85], v[82:85], v[86:89], 0
	s_waitcnt lgkmcnt(0)
	v_mfma_f32_16x16x32_bf16 v[82:85], v[90:93], v[94:97], v[82:85]
	ds_read_b128 v[90:93], v79 offset:61056
	ds_read_b128 v[98:101], v79 offset:13184
	s_waitcnt lgkmcnt(0)
	v_mfma_f32_16x16x32_bf16 v[82:85], v[90:93], v[98:101], v[82:85]
	ds_read_b128 v[90:93], v79 offset:61120
	ds_read_b128 v[102:105], v79 offset:13248
	ds_read_b128 v[106:109], v79 offset:65344
	ds_read_b128 v[110:113], v80 offset:34880
	s_waitcnt lgkmcnt(2)
	v_mfma_f32_16x16x32_bf16 v[82:85], v[90:93], v[102:105], v[82:85]
	ds_read_b128 v[90:93], v79 offset:65280
	s_waitcnt lgkmcnt(0)
	v_mfma_f32_16x16x32_bf16 v[90:93], v[90:93], v[86:89], 0
	s_nop 4
	v_cvt_pk_bf16_f32 v82, v82, v83
	v_cvt_pk_bf16_f32 v83, v84, v85
	v_mfma_f32_16x16x32_bf16 v[90:93], v[106:109], v[94:97], v[90:93]
	ds_read_b128 v[106:109], v79 offset:65408
	s_waitcnt lgkmcnt(0)
	v_mfma_f32_16x16x32_bf16 v[90:93], v[106:109], v[98:101], v[90:93]
	ds_read_b128 v[106:109], v79 offset:65472
	s_waitcnt lgkmcnt(0)
	v_mfma_f32_16x16x32_bf16 v[90:93], v[106:109], v[102:105], v[90:93]
	ds_read_b128 v[106:109], v80 offset:34816
	s_nop 6
	v_cvt_pk_bf16_f32 v84, v90, v91
	s_waitcnt lgkmcnt(0)
	v_mfma_f32_16x16x32_bf16 v[106:109], v[106:109], v[86:89], 0
	v_cvt_pk_bf16_f32 v85, v92, v93
	v_mfma_f32_16x16x32_bf16 v[106:109], v[110:113], v[94:97], v[106:109]
	ds_read_b128 v[110:113], v80 offset:34944
	s_waitcnt lgkmcnt(0)
	v_mfma_f32_16x16x32_bf16 v[106:109], v[110:113], v[98:101], v[106:109]
	ds_read_b128 v[110:113], v80 offset:35008
	s_waitcnt lgkmcnt(0)
	v_mfma_f32_16x16x32_bf16 v[106:109], v[110:113], v[102:105], v[106:109]
	ds_read_b128 v[110:113], v80 offset:39168
	s_waitcnt lgkmcnt(0)
	v_mfma_f32_16x16x32_bf16 v[86:89], v[110:113], v[86:89], 0
	ds_read_b128 v[110:113], v80 offset:39232
	s_waitcnt lgkmcnt(0)
	v_mfma_f32_16x16x32_bf16 v[86:89], v[110:113], v[94:97], v[86:89]
	ds_read_b128 v[94:97], v80 offset:39296
	s_waitcnt lgkmcnt(0)
	v_mfma_f32_16x16x32_bf16 v[86:89], v[94:97], v[98:101], v[86:89]
	ds_read_b128 v[94:97], v80 offset:39360
	s_waitcnt lgkmcnt(0)
	v_mfma_f32_16x16x32_bf16 v[86:89], v[94:97], v[102:105], v[86:89]
	s_nop 7
	v_cndmask_b32_e64 v86, v86, 0, s[20:21]
	v_mfma_f32_16x16x32_bf16 v[4:7], v[12:15], v[82:85], v[4:7]
	v_cndmask_b32_e64 v87, 0, v87, s[22:23]
	v_cndmask_b32_e64 v88, v88, 0, s[24:25]
	v_cndmask_b32_e64 v89, v89, 0, s[26:27]
	v_cvt_pk_bf16_f32 v12, v106, v107
	v_cvt_pk_bf16_f32 v13, v108, v109
	v_cvt_pk_bf16_f32 v14, v86, v87
	v_cvt_pk_bf16_f32 v15, v88, v89
	s_nop 1
	v_mfma_f32_16x16x32_bf16 v[4:7], v[24:27], v[12:15], v[4:7]
	v_or_b32_e32 v12, s35, v52
	v_ashrrev_i32_e32 v13, 31, v12
	v_lshl_add_u64 v[14:15], s[52:53], 2, v[28:29]
	v_lshlrev_b64 v[24:25], 12, v[12:13]
	v_lshl_add_u64 v[24:25], v[14:15], 0, v[24:25]
	global_store_dwordx4 v[24:25], v[8:11], off
	s_nop 1
	v_or_b32_e32 v8, 16, v12
	v_ashrrev_i32_e32 v9, 31, v8
	v_lshlrev_b64 v[8:9], 12, v[8:9]
	v_lshl_add_u64 v[8:9], v[14:15], 0, v[8:9]
	global_store_dwordx4 v[8:9], v[16:19], off
	v_or_b32_e32 v8, 32, v12
	v_ashrrev_i32_e32 v9, 31, v8
	v_lshlrev_b64 v[8:9], 12, v[8:9]
	v_lshl_add_u64 v[8:9], v[14:15], 0, v[8:9]
	global_store_dwordx4 v[8:9], v[20:23], off
	v_or_b32_e32 v8, 48, v12
	v_ashrrev_i32_e32 v9, 31, v8
	v_lshlrev_b64 v[8:9], 12, v[8:9]
	v_lshl_add_u64 v[8:9], v[14:15], 0, v[8:9]
	global_store_dwordx4 v[8:9], v[4:7], off
	s_cbranch_scc0 .LBB0_887
